# P8 epilogue: carry-chain pad restored (s_nop 1 between v_add_co and v_addc), scalar f32 fma chain
# speedup vs baseline: 1.0065x; 1.0020x over previous
; __device__ __forceinline__ float sigm(float x) { return __builtin_amdgcn_rcpf(1.0f + __expf(-x)); }
;     __device__ __forceinline__ void operator()(const f32x4 (&acc)[2][2][4][2], const pg8::Unit& u, int wr, int wc, int fr, int fq) const {
;         const int reg = u.pn >> 2;
;         const int row0 = u.pm * 256 + wr * 64 + fr, cc0 = (u.pn & 3) * 256 + wc * 32 + 8 * fq;
;         f16_t* base = L + (size_t)reg * MT * RW + (size_t)row0 * RW + cc0;
;         const float* bp = bias + reg * RW + cc0;
;         const float sc = reg < 2 ? 0.6065306597126334f : 1.0f;
;         const bool act = reg < 4;
;         f32x4 bva[2][2];
; #pragma unroll
;         for (int bj = 0; bj < 2; ++bj)
; #pragma unroll
;             for (int n = 0; n < 2; ++n) bva[bj][n] = *(const f32x4*)(bp + bj * 128 + 4 * n);
; #pragma unroll
;         for (int bj = 0; bj < 2; ++bj)
; #pragma unroll
;             for (int n = 0; n < 2; ++n) {
;                 const f32x4 bv = bva[bj][n];
; #pragma unroll
;                 for (int ai = 0; ai < 2; ++ai)
; #pragma unroll
;                     for (int m = 0; m < 4; ++m) {
;                         f32x4 v = acc[ai][bj][m][n] + bv;
; #pragma unroll
;                         for (int j = 0; j < 4; ++j) { const float sg = sc * sigm(v[j]); v[j] = act ? sg : v[j]; }
;                         u32x2 w; w.x = pk_f16(v[0], v[1]); w.y = pk_f16(v[2], v[3]);
;                         *(u32x2*)(base + (size_t)(ai * 128 + m * 16) * RW + bj * 128 + 4 * n) = w;
;                     }
.LBB0_694:
	s_lshl_b32 s0, s33, 8
	s_ashr_i32 s15, s33, 2
	s_and_b32 s0, s0, 0x300
	v_or_b32_e32 v98, s0, v166
	s_lshl_b32 s0, s15, 10
	s_ashr_i32 s1, s0, 31
	s_lshl_b64 s[0:1], s[0:1], 2
	s_add_u32 s0, s62, s0
	s_addc_u32 s1, s63, s1
	v_lshlrev_b32_e32 v132, 2, v98
	global_load_dwordx4 v[140:143], v132, s[0:1]
	global_load_dwordx4 v[136:139], v132, s[0:1] offset:16
	v_lshl_add_u32 v96, s20, 8, v164
	s_mul_i32 s20, s15, 0x4400000
	v_ashrrev_i32_e32 v97, 31, v96
	s_cmp_lt_i32 s15, 2
	s_mul_hi_i32 s17, s15, 0x4400000
	v_lshlrev_b64 v[162:163], 11, v[96:97]
	v_lshlrev_b32_e32 v152, 1, v98
	global_load_dwordx4 v[96:99], v132, s[0:1] offset:528
	s_nop 0
	global_load_dwordx4 v[132:135], v132, s[0:1] offset:512
	s_cselect_b64 vcc, -1, 0
	s_add_u32 s0, s60, s20
	s_addc_u32 s1, s61, s17
	v_lshl_add_u64 v[162:163], s[0:1], 0, v[162:163]
	v_lshl_add_u64 v[162:163], v[162:163], 0, v[152:153]
	v_cndmask_b32_e32 v171, 1.0, v170, vcc
	s_cmp_lt_i32 s15, 4
	s_cselect_b64 vcc, -1, 0
	s_mov_b32 s33, s14
	s_mov_b32 s20, s16
	s_mov_b64 s[22:23], s[4:5]
	s_mov_b64 s[36:37], s[18:19]
	s_waitcnt vmcnt(0)
	s_cbranch_vccz .Lp8_noact
	v_rcp_f32_e32 v152, v171
	v_mov_b32_e32 v182, 0xbfb8aa3b
	v_mul_f32_e32 v140, 0xbfb8aa3b, v140
	v_mul_f32_e32 v141, 0xbfb8aa3b, v141
	v_mul_f32_e32 v142, 0xbfb8aa3b, v142
	v_mul_f32_e32 v143, 0xbfb8aa3b, v143
	v_mul_f32_e32 v136, 0xbfb8aa3b, v136
	v_mul_f32_e32 v137, 0xbfb8aa3b, v137
	v_mul_f32_e32 v138, 0xbfb8aa3b, v138
	v_mul_f32_e32 v139, 0xbfb8aa3b, v139
	v_mul_f32_e32 v132, 0xbfb8aa3b, v132
	v_mul_f32_e32 v133, 0xbfb8aa3b, v133
	v_mul_f32_e32 v134, 0xbfb8aa3b, v134
	v_mul_f32_e32 v135, 0xbfb8aa3b, v135
	v_mul_f32_e32 v96, 0xbfb8aa3b, v96
	v_mul_f32_e32 v97, 0xbfb8aa3b, v97
	v_mul_f32_e32 v98, 0xbfb8aa3b, v98
	v_mul_f32_e32 v99, 0xbfb8aa3b, v99
	v_fma_f32 v128, v128, v182, v140
	v_fma_f32 v129, v129, v182, v141
	v_fma_f32 v130, v130, v182, v142
	v_fma_f32 v131, v131, v182, v143
	v_fma_f32 v92, v92, v182, v136
	v_fma_f32 v93, v93, v182, v137
	v_fma_f32 v94, v94, v182, v138
	v_fma_f32 v95, v95, v182, v139
	v_exp_f32_e32 v128, v128
	v_exp_f32_e32 v129, v129
	v_exp_f32_e32 v130, v130
	v_exp_f32_e32 v131, v131
	v_exp_f32_e32 v92, v92
	v_exp_f32_e32 v93, v93
	v_exp_f32_e32 v94, v94
	v_exp_f32_e32 v95, v95
	v_fma_f32 v128, v128, v152, v152
	v_fma_f32 v129, v129, v152, v152
	v_fma_f32 v130, v130, v152, v152
	v_fma_f32 v131, v131, v152, v152
	v_fma_f32 v92, v92, v152, v152
	v_fma_f32 v93, v93, v152, v152
	v_fma_f32 v94, v94, v152, v152
	v_fma_f32 v95, v95, v152, v152
	v_rcp_f32_e32 v128, v128
	v_rcp_f32_e32 v129, v129
	v_rcp_f32_e32 v130, v130
	v_rcp_f32_e32 v131, v131
	v_rcp_f32_e32 v92, v92
	v_rcp_f32_e32 v93, v93
	v_rcp_f32_e32 v94, v94
	v_rcp_f32_e32 v95, v95
	v_cvt_pk_f16_f32 v128, v128, v129
	v_cvt_pk_f16_f32 v129, v130, v131
	v_cvt_pk_f16_f32 v130, v92, v93
	v_cvt_pk_f16_f32 v131, v94, v95
	global_store_dwordx4 v[162:163], v[128:131], off
	v_fma_f32 v60, v60, v182, v132
	v_fma_f32 v61, v61, v182, v133
	v_fma_f32 v62, v62, v182, v134
	v_fma_f32 v63, v63, v182, v135
	v_fma_f32 v28, v28, v182, v96
	v_fma_f32 v29, v29, v182, v97
	v_fma_f32 v30, v30, v182, v98
	v_fma_f32 v31, v31, v182, v99
	v_exp_f32_e32 v60, v60
	v_exp_f32_e32 v61, v61
	v_exp_f32_e32 v62, v62
	v_exp_f32_e32 v63, v63
	v_exp_f32_e32 v28, v28
	v_exp_f32_e32 v29, v29
	v_exp_f32_e32 v30, v30
	v_exp_f32_e32 v31, v31
	v_fma_f32 v60, v60, v152, v152
	v_fma_f32 v61, v61, v152, v152
	v_fma_f32 v62, v62, v152, v152
	v_fma_f32 v63, v63, v152, v152
	v_fma_f32 v28, v28, v152, v152
	v_fma_f32 v29, v29, v152, v152
	v_fma_f32 v30, v30, v152, v152
	v_fma_f32 v31, v31, v152, v152
	v_rcp_f32_e32 v60, v60
	v_rcp_f32_e32 v61, v61
	v_rcp_f32_e32 v62, v62
	v_rcp_f32_e32 v63, v63
	v_rcp_f32_e32 v28, v28
	v_rcp_f32_e32 v29, v29
	v_rcp_f32_e32 v30, v30
	v_rcp_f32_e32 v31, v31
	v_cvt_pk_f16_f32 v60, v60, v61
	v_cvt_pk_f16_f32 v61, v62, v63
	v_cvt_pk_f16_f32 v62, v28, v29
	v_cvt_pk_f16_f32 v63, v30, v31
	global_store_dwordx4 v[162:163], v[60:63], off offset:256
	v_add_co_u32_e64 v172, s[0:1], s71, v162
	s_nop 1
	v_addc_co_u32_e64 v173, s[0:1], 0, v163, s[0:1]
	v_fma_f32 v124, v124, v182, v140
	v_fma_f32 v125, v125, v182, v141
	v_fma_f32 v126, v126, v182, v142
	v_fma_f32 v127, v127, v182, v143
	v_fma_f32 v88, v88, v182, v136
	v_fma_f32 v89, v89, v182, v137
	v_fma_f32 v90, v90, v182, v138
	v_fma_f32 v91, v91, v182, v139
	v_exp_f32_e32 v124, v124
	v_exp_f32_e32 v125, v125
	v_exp_f32_e32 v126, v126
	v_exp_f32_e32 v127, v127
	v_exp_f32_e32 v88, v88
	v_exp_f32_e32 v89, v89
	v_exp_f32_e32 v90, v90
	v_exp_f32_e32 v91, v91
	v_fma_f32 v124, v124, v152, v152
	v_fma_f32 v125, v125, v152, v152
	v_fma_f32 v126, v126, v152, v152
	v_fma_f32 v127, v127, v152, v152
	v_fma_f32 v88, v88, v152, v152
	v_fma_f32 v89, v89, v152, v152
	v_fma_f32 v90, v90, v152, v152
	v_fma_f32 v91, v91, v152, v152
	v_rcp_f32_e32 v124, v124
	v_rcp_f32_e32 v125, v125
	v_rcp_f32_e32 v126, v126
	v_rcp_f32_e32 v127, v127
	v_rcp_f32_e32 v88, v88
	v_rcp_f32_e32 v89, v89
	v_rcp_f32_e32 v90, v90
	v_rcp_f32_e32 v91, v91
	v_cvt_pk_f16_f32 v124, v124, v125
	v_cvt_pk_f16_f32 v125, v126, v127
	v_cvt_pk_f16_f32 v126, v88, v89
	v_cvt_pk_f16_f32 v127, v90, v91
	global_store_dwordx4 v[172:173], v[124:127], off
	v_fma_f32 v56, v56, v182, v132
	v_fma_f32 v57, v57, v182, v133
	v_fma_f32 v58, v58, v182, v134
	v_fma_f32 v59, v59, v182, v135
	v_fma_f32 v24, v24, v182, v96
	v_fma_f32 v25, v25, v182, v97
	v_fma_f32 v26, v26, v182, v98
	v_fma_f32 v27, v27, v182, v99
	v_exp_f32_e32 v56, v56
	v_exp_f32_e32 v57, v57
	v_exp_f32_e32 v58, v58
	v_exp_f32_e32 v59, v59
	v_exp_f32_e32 v24, v24
	v_exp_f32_e32 v25, v25
	v_exp_f32_e32 v26, v26
	v_exp_f32_e32 v27, v27
; __device__ __forceinline__ float sigm(float x) { return __builtin_amdgcn_rcpf(1.0f + __expf(-x)); }
;     __device__ __forceinline__ void operator()(const f32x4 (&acc)[2][2][4][2], const pg8::Unit& u, int wr, int wc, int fr, int fq) const {
;     ...
;                 for (int ai = 0; ai < 2; ++ai)
; #pragma unroll
;                     for (int m = 0; m < 4; ++m) {
;                         f32x4 v = acc[ai][bj][m][n] + bv;
; #pragma unroll
;                         for (int j = 0; j < 4; ++j) { const float sg = sc * sigm(v[j]); v[j] = act ? sg : v[j]; }
;                         u32x2 w; w.x = pk_f16(v[0], v[1]); w.y = pk_f16(v[2], v[3]);
;                         *(u32x2*)(base + (size_t)(ai * 128 + m * 16) * RW + bj * 128 + 4 * n) = w;
;                     }
	v_fma_f32 v56, v56, v152, v152
	v_fma_f32 v57, v57, v152, v152
	v_fma_f32 v58, v58, v152, v152
	v_fma_f32 v59, v59, v152, v152
	v_fma_f32 v24, v24, v152, v152
	v_fma_f32 v25, v25, v152, v152
	v_fma_f32 v26, v26, v152, v152
	v_fma_f32 v27, v27, v152, v152
	v_rcp_f32_e32 v56, v56
	v_rcp_f32_e32 v57, v57
	v_rcp_f32_e32 v58, v58
	v_rcp_f32_e32 v59, v59
	v_rcp_f32_e32 v24, v24
	v_rcp_f32_e32 v25, v25
	v_rcp_f32_e32 v26, v26
	v_rcp_f32_e32 v27, v27
	v_cvt_pk_f16_f32 v56, v56, v57
	v_cvt_pk_f16_f32 v57, v58, v59
	v_cvt_pk_f16_f32 v58, v24, v25
	v_cvt_pk_f16_f32 v59, v26, v27
	global_store_dwordx4 v[172:173], v[56:59], off offset:256
	s_mov_b32 s0, 0x10000
	v_add_co_u32_e64 v174, s[0:1], s0, v162
	s_nop 1
	v_addc_co_u32_e64 v175, s[0:1], 0, v163, s[0:1]
	v_fma_f32 v120, v120, v182, v140
	v_fma_f32 v121, v121, v182, v141
	v_fma_f32 v122, v122, v182, v142
	v_fma_f32 v123, v123, v182, v143
	v_fma_f32 v84, v84, v182, v136
	v_fma_f32 v85, v85, v182, v137
	v_fma_f32 v86, v86, v182, v138
	v_fma_f32 v87, v87, v182, v139
	v_exp_f32_e32 v120, v120
	v_exp_f32_e32 v121, v121
	v_exp_f32_e32 v122, v122
	v_exp_f32_e32 v123, v123
	v_exp_f32_e32 v84, v84
	v_exp_f32_e32 v85, v85
	v_exp_f32_e32 v86, v86
	v_exp_f32_e32 v87, v87
	v_fma_f32 v120, v120, v152, v152
	v_fma_f32 v121, v121, v152, v152
	v_fma_f32 v122, v122, v152, v152
	v_fma_f32 v123, v123, v152, v152
	v_fma_f32 v84, v84, v152, v152
	v_fma_f32 v85, v85, v152, v152
	v_fma_f32 v86, v86, v152, v152
	v_fma_f32 v87, v87, v152, v152
	v_rcp_f32_e32 v120, v120
	v_rcp_f32_e32 v121, v121
	v_rcp_f32_e32 v122, v122
	v_rcp_f32_e32 v123, v123
	v_rcp_f32_e32 v84, v84
	v_rcp_f32_e32 v85, v85
	v_rcp_f32_e32 v86, v86
	v_rcp_f32_e32 v87, v87
	v_cvt_pk_f16_f32 v120, v120, v121
	v_cvt_pk_f16_f32 v121, v122, v123
	v_cvt_pk_f16_f32 v122, v84, v85
	v_cvt_pk_f16_f32 v123, v86, v87
	global_store_dwordx4 v[174:175], v[120:123], off
	v_fma_f32 v52, v52, v182, v132
	v_fma_f32 v53, v53, v182, v133
	v_fma_f32 v54, v54, v182, v134
	v_fma_f32 v55, v55, v182, v135
	v_fma_f32 v20, v20, v182, v96
	v_fma_f32 v21, v21, v182, v97
	v_fma_f32 v22, v22, v182, v98
	v_fma_f32 v23, v23, v182, v99
	v_exp_f32_e32 v52, v52
	v_exp_f32_e32 v53, v53
	v_exp_f32_e32 v54, v54
	v_exp_f32_e32 v55, v55
	v_exp_f32_e32 v20, v20
	v_exp_f32_e32 v21, v21
	v_exp_f32_e32 v22, v22
	v_exp_f32_e32 v23, v23
	v_fma_f32 v52, v52, v152, v152
	v_fma_f32 v53, v53, v152, v152
	v_fma_f32 v54, v54, v152, v152
	v_fma_f32 v55, v55, v152, v152
	v_fma_f32 v20, v20, v152, v152
	v_fma_f32 v21, v21, v152, v152
	v_fma_f32 v22, v22, v152, v152
	v_fma_f32 v23, v23, v152, v152
	v_rcp_f32_e32 v52, v52
	v_rcp_f32_e32 v53, v53
	v_rcp_f32_e32 v54, v54
	v_rcp_f32_e32 v55, v55
	v_rcp_f32_e32 v20, v20
	v_rcp_f32_e32 v21, v21
	v_rcp_f32_e32 v22, v22
	v_rcp_f32_e32 v23, v23
	v_cvt_pk_f16_f32 v52, v52, v53
	v_cvt_pk_f16_f32 v53, v54, v55
	v_cvt_pk_f16_f32 v54, v20, v21
	v_cvt_pk_f16_f32 v55, v22, v23
	global_store_dwordx4 v[174:175], v[52:55], off offset:256
	s_mov_b32 s0, 0x18000
	v_add_co_u32_e64 v172, s[0:1], s0, v162
	s_nop 1
	v_addc_co_u32_e64 v173, s[0:1], 0, v163, s[0:1]
	v_fma_f32 v116, v116, v182, v140
	v_fma_f32 v117, v117, v182, v141
	v_fma_f32 v118, v118, v182, v142
	v_fma_f32 v119, v119, v182, v143
	v_fma_f32 v80, v80, v182, v136
	v_fma_f32 v81, v81, v182, v137
	v_fma_f32 v82, v82, v182, v138
	v_fma_f32 v83, v83, v182, v139
	v_exp_f32_e32 v116, v116
	v_exp_f32_e32 v117, v117
	v_exp_f32_e32 v118, v118
	v_exp_f32_e32 v119, v119
	v_exp_f32_e32 v80, v80
	v_exp_f32_e32 v81, v81
	v_exp_f32_e32 v82, v82
	v_exp_f32_e32 v83, v83
	v_fma_f32 v116, v116, v152, v152
	v_fma_f32 v117, v117, v152, v152
	v_fma_f32 v118, v118, v152, v152
	v_fma_f32 v119, v119, v152, v152
	v_fma_f32 v80, v80, v152, v152
	v_fma_f32 v81, v81, v152, v152
	v_fma_f32 v82, v82, v152, v152
	v_fma_f32 v83, v83, v152, v152
	v_rcp_f32_e32 v116, v116
	v_rcp_f32_e32 v117, v117
	v_rcp_f32_e32 v118, v118
	v_rcp_f32_e32 v119, v119
	v_rcp_f32_e32 v80, v80
	v_rcp_f32_e32 v81, v81
	v_rcp_f32_e32 v82, v82
	v_rcp_f32_e32 v83, v83
	v_cvt_pk_f16_f32 v116, v116, v117
	v_cvt_pk_f16_f32 v117, v118, v119
	v_cvt_pk_f16_f32 v118, v80, v81
	v_cvt_pk_f16_f32 v119, v82, v83
	global_store_dwordx4 v[172:173], v[116:119], off
	v_fma_f32 v48, v48, v182, v132
	v_fma_f32 v49, v49, v182, v133
	v_fma_f32 v50, v50, v182, v134
	v_fma_f32 v51, v51, v182, v135
	v_fma_f32 v16, v16, v182, v96
	v_fma_f32 v17, v17, v182, v97
	v_fma_f32 v18, v18, v182, v98
	v_fma_f32 v19, v19, v182, v99
	v_exp_f32_e32 v48, v48
	v_exp_f32_e32 v49, v49
	v_exp_f32_e32 v50, v50
	v_exp_f32_e32 v51, v51
	v_exp_f32_e32 v16, v16
	v_exp_f32_e32 v17, v17
	v_exp_f32_e32 v18, v18
	v_exp_f32_e32 v19, v19
	v_fma_f32 v48, v48, v152, v152
	v_fma_f32 v49, v49, v152, v152
	v_fma_f32 v50, v50, v152, v152
	v_fma_f32 v51, v51, v152, v152
	v_fma_f32 v16, v16, v152, v152
	v_fma_f32 v17, v17, v152, v152
	v_fma_f32 v18, v18, v152, v152
	v_fma_f32 v19, v19, v152, v152
	v_rcp_f32_e32 v48, v48
	v_rcp_f32_e32 v49, v49
	v_rcp_f32_e32 v50, v50
	v_rcp_f32_e32 v51, v51
	v_rcp_f32_e32 v16, v16
	v_rcp_f32_e32 v17, v17
	v_rcp_f32_e32 v18, v18
	v_rcp_f32_e32 v19, v19
	v_cvt_pk_f16_f32 v48, v48, v49
	v_cvt_pk_f16_f32 v49, v50, v51
	v_cvt_pk_f16_f32 v50, v16, v17
	v_cvt_pk_f16_f32 v51, v18, v19
	global_store_dwordx4 v[172:173], v[48:51], off offset:256
	v_add_co_u32_e64 v174, s[0:1], s85, v162
	s_nop 1
	v_addc_co_u32_e64 v175, s[0:1], 0, v163, s[0:1]
	v_fma_f32 v112, v112, v182, v140
	v_fma_f32 v113, v113, v182, v141
	v_fma_f32 v114, v114, v182, v142
	v_fma_f32 v115, v115, v182, v143
	v_fma_f32 v76, v76, v182, v136
	v_fma_f32 v77, v77, v182, v137
	v_fma_f32 v78, v78, v182, v138
	v_fma_f32 v79, v79, v182, v139
; __device__ __forceinline__ float sigm(float x) { return __builtin_amdgcn_rcpf(1.0f + __expf(-x)); }
;     __device__ __forceinline__ void operator()(const f32x4 (&acc)[2][2][4][2], const pg8::Unit& u, int wr, int wc, int fr, int fq) const {
;     ...
;                 for (int ai = 0; ai < 2; ++ai)
; #pragma unroll
;                     for (int m = 0; m < 4; ++m) {
;                         f32x4 v = acc[ai][bj][m][n] + bv;
; #pragma unroll
;                         for (int j = 0; j < 4; ++j) { const float sg = sc * sigm(v[j]); v[j] = act ? sg : v[j]; }
;                         u32x2 w; w.x = pk_f16(v[0], v[1]); w.y = pk_f16(v[2], v[3]);
;                         *(u32x2*)(base + (size_t)(ai * 128 + m * 16) * RW + bj * 128 + 4 * n) = w;
;                     }
	v_exp_f32_e32 v112, v112
	v_exp_f32_e32 v113, v113
	v_exp_f32_e32 v114, v114
	v_exp_f32_e32 v115, v115
	v_exp_f32_e32 v76, v76
	v_exp_f32_e32 v77, v77
	v_exp_f32_e32 v78, v78
	v_exp_f32_e32 v79, v79
	v_fma_f32 v112, v112, v152, v152
	v_fma_f32 v113, v113, v152, v152
	v_fma_f32 v114, v114, v152, v152
	v_fma_f32 v115, v115, v152, v152
	v_fma_f32 v76, v76, v152, v152
	v_fma_f32 v77, v77, v152, v152
	v_fma_f32 v78, v78, v152, v152
	v_fma_f32 v79, v79, v152, v152
	v_rcp_f32_e32 v112, v112
	v_rcp_f32_e32 v113, v113
	v_rcp_f32_e32 v114, v114
	v_rcp_f32_e32 v115, v115
	v_rcp_f32_e32 v76, v76
	v_rcp_f32_e32 v77, v77
	v_rcp_f32_e32 v78, v78
	v_rcp_f32_e32 v79, v79
	v_cvt_pk_f16_f32 v112, v112, v113
	v_cvt_pk_f16_f32 v113, v114, v115
	v_cvt_pk_f16_f32 v114, v76, v77
	v_cvt_pk_f16_f32 v115, v78, v79
	global_store_dwordx4 v[174:175], v[112:115], off
	v_fma_f32 v44, v44, v182, v132
	v_fma_f32 v45, v45, v182, v133
	v_fma_f32 v46, v46, v182, v134
	v_fma_f32 v47, v47, v182, v135
	v_fma_f32 v12, v12, v182, v96
	v_fma_f32 v13, v13, v182, v97
	v_fma_f32 v14, v14, v182, v98
	v_fma_f32 v15, v15, v182, v99
	v_exp_f32_e32 v44, v44
	v_exp_f32_e32 v45, v45
	v_exp_f32_e32 v46, v46
	v_exp_f32_e32 v47, v47
	v_exp_f32_e32 v12, v12
	v_exp_f32_e32 v13, v13
	v_exp_f32_e32 v14, v14
	v_exp_f32_e32 v15, v15
	v_fma_f32 v44, v44, v152, v152
	v_fma_f32 v45, v45, v152, v152
	v_fma_f32 v46, v46, v152, v152
	v_fma_f32 v47, v47, v152, v152
	v_fma_f32 v12, v12, v152, v152
	v_fma_f32 v13, v13, v152, v152
	v_fma_f32 v14, v14, v152, v152
	v_fma_f32 v15, v15, v152, v152
	v_rcp_f32_e32 v44, v44
	v_rcp_f32_e32 v45, v45
	v_rcp_f32_e32 v46, v46
	v_rcp_f32_e32 v47, v47
	v_rcp_f32_e32 v12, v12
	v_rcp_f32_e32 v13, v13
	v_rcp_f32_e32 v14, v14
	v_rcp_f32_e32 v15, v15
	v_cvt_pk_f16_f32 v44, v44, v45
	v_cvt_pk_f16_f32 v45, v46, v47
	v_cvt_pk_f16_f32 v46, v12, v13
	v_cvt_pk_f16_f32 v47, v14, v15
	global_store_dwordx4 v[174:175], v[44:47], off offset:256
	v_add_co_u32_e64 v172, s[0:1], s94, v162
	s_nop 1
	v_addc_co_u32_e64 v173, s[0:1], 0, v163, s[0:1]
	v_fma_f32 v108, v108, v182, v140
	v_fma_f32 v109, v109, v182, v141
	v_fma_f32 v110, v110, v182, v142
	v_fma_f32 v111, v111, v182, v143
	v_fma_f32 v72, v72, v182, v136
	v_fma_f32 v73, v73, v182, v137
	v_fma_f32 v74, v74, v182, v138
	v_fma_f32 v75, v75, v182, v139
	v_exp_f32_e32 v108, v108
	v_exp_f32_e32 v109, v109
	v_exp_f32_e32 v110, v110
	v_exp_f32_e32 v111, v111
	v_exp_f32_e32 v72, v72
	v_exp_f32_e32 v73, v73
	v_exp_f32_e32 v74, v74
	v_exp_f32_e32 v75, v75
	v_fma_f32 v108, v108, v152, v152
	v_fma_f32 v109, v109, v152, v152
	v_fma_f32 v110, v110, v152, v152
	v_fma_f32 v111, v111, v152, v152
	v_fma_f32 v72, v72, v152, v152
	v_fma_f32 v73, v73, v152, v152
	v_fma_f32 v74, v74, v152, v152
	v_fma_f32 v75, v75, v152, v152
	v_rcp_f32_e32 v108, v108
	v_rcp_f32_e32 v109, v109
	v_rcp_f32_e32 v110, v110
	v_rcp_f32_e32 v111, v111
	v_rcp_f32_e32 v72, v72
	v_rcp_f32_e32 v73, v73
	v_rcp_f32_e32 v74, v74
	v_rcp_f32_e32 v75, v75
	v_cvt_pk_f16_f32 v108, v108, v109
	v_cvt_pk_f16_f32 v109, v110, v111
	v_cvt_pk_f16_f32 v110, v72, v73
	v_cvt_pk_f16_f32 v111, v74, v75
	global_store_dwordx4 v[172:173], v[108:111], off
	v_fma_f32 v40, v40, v182, v132
	v_fma_f32 v41, v41, v182, v133
	v_fma_f32 v42, v42, v182, v134
	v_fma_f32 v43, v43, v182, v135
	v_fma_f32 v8, v8, v182, v96
	v_fma_f32 v9, v9, v182, v97
	v_fma_f32 v10, v10, v182, v98
	v_fma_f32 v11, v11, v182, v99
	v_exp_f32_e32 v40, v40
	v_exp_f32_e32 v41, v41
	v_exp_f32_e32 v42, v42
	v_exp_f32_e32 v43, v43
	v_exp_f32_e32 v8, v8
	v_exp_f32_e32 v9, v9
	v_exp_f32_e32 v10, v10
	v_exp_f32_e32 v11, v11
	v_fma_f32 v40, v40, v152, v152
	v_fma_f32 v41, v41, v152, v152
	v_fma_f32 v42, v42, v152, v152
	v_fma_f32 v43, v43, v152, v152
	v_fma_f32 v8, v8, v152, v152
	v_fma_f32 v9, v9, v152, v152
	v_fma_f32 v10, v10, v152, v152
	v_fma_f32 v11, v11, v152, v152
	v_rcp_f32_e32 v40, v40
	v_rcp_f32_e32 v41, v41
	v_rcp_f32_e32 v42, v42
	v_rcp_f32_e32 v43, v43
	v_rcp_f32_e32 v8, v8
	v_rcp_f32_e32 v9, v9
	v_rcp_f32_e32 v10, v10
	v_rcp_f32_e32 v11, v11
	v_cvt_pk_f16_f32 v40, v40, v41
	v_cvt_pk_f16_f32 v41, v42, v43
	v_cvt_pk_f16_f32 v42, v8, v9
	v_cvt_pk_f16_f32 v43, v10, v11
	global_store_dwordx4 v[172:173], v[40:43], off offset:256
	v_add_co_u32_e64 v174, s[0:1], s95, v162
	s_nop 1
	v_addc_co_u32_e64 v175, s[0:1], 0, v163, s[0:1]
	v_fma_f32 v104, v104, v182, v140
	v_fma_f32 v105, v105, v182, v141
	v_fma_f32 v106, v106, v182, v142
	v_fma_f32 v107, v107, v182, v143
	v_fma_f32 v68, v68, v182, v136
	v_fma_f32 v69, v69, v182, v137
	v_fma_f32 v70, v70, v182, v138
	v_fma_f32 v71, v71, v182, v139
	v_exp_f32_e32 v104, v104
	v_exp_f32_e32 v105, v105
	v_exp_f32_e32 v106, v106
	v_exp_f32_e32 v107, v107
	v_exp_f32_e32 v68, v68
	v_exp_f32_e32 v69, v69
	v_exp_f32_e32 v70, v70
	v_exp_f32_e32 v71, v71
	v_fma_f32 v104, v104, v152, v152
	v_fma_f32 v105, v105, v152, v152
	v_fma_f32 v106, v106, v152, v152
	v_fma_f32 v107, v107, v152, v152
	v_fma_f32 v68, v68, v152, v152
	v_fma_f32 v69, v69, v152, v152
	v_fma_f32 v70, v70, v152, v152
	v_fma_f32 v71, v71, v152, v152
	v_rcp_f32_e32 v104, v104
	v_rcp_f32_e32 v105, v105
	v_rcp_f32_e32 v106, v106
	v_rcp_f32_e32 v107, v107
	v_rcp_f32_e32 v68, v68
	v_rcp_f32_e32 v69, v69
	v_rcp_f32_e32 v70, v70
	v_rcp_f32_e32 v71, v71
	v_cvt_pk_f16_f32 v104, v104, v105
	v_cvt_pk_f16_f32 v105, v106, v107
	v_cvt_pk_f16_f32 v106, v68, v69
	v_cvt_pk_f16_f32 v107, v70, v71
	global_store_dwordx4 v[174:175], v[104:107], off
	v_fma_f32 v36, v36, v182, v132
	v_fma_f32 v37, v37, v182, v133
	v_fma_f32 v38, v38, v182, v134
	v_fma_f32 v39, v39, v182, v135
	v_fma_f32 v4, v4, v182, v96
	v_fma_f32 v5, v5, v182, v97
	v_fma_f32 v6, v6, v182, v98
; __device__ __forceinline__ float sigm(float x) { return __builtin_amdgcn_rcpf(1.0f + __expf(-x)); }
;     __device__ __forceinline__ void operator()(const f32x4 (&acc)[2][2][4][2], const pg8::Unit& u, int wr, int wc, int fr, int fq) const {
;     ...
;             for (int n = 0; n < 2; ++n) bva[bj][n] = *(const f32x4*)(bp + bj * 128 + 4 * n);
; #pragma unroll
;         for (int bj = 0; bj < 2; ++bj)
; #pragma unroll
;             for (int n = 0; n < 2; ++n) {
;                 const f32x4 bv = bva[bj][n];
; #pragma unroll
;                 for (int ai = 0; ai < 2; ++ai)
; #pragma unroll
;                     for (int m = 0; m < 4; ++m) {
;                         f32x4 v = acc[ai][bj][m][n] + bv;
; #pragma unroll
;                         for (int j = 0; j < 4; ++j) { const float sg = sc * sigm(v[j]); v[j] = act ? sg : v[j]; }
;                         u32x2 w; w.x = pk_f16(v[0], v[1]); w.y = pk_f16(v[2], v[3]);
;                         *(u32x2*)(base + (size_t)(ai * 128 + m * 16) * RW + bj * 128 + 4 * n) = w;
;                     }
	v_fma_f32 v7, v7, v182, v99
	v_exp_f32_e32 v36, v36
	v_exp_f32_e32 v37, v37
	v_exp_f32_e32 v38, v38
	v_exp_f32_e32 v39, v39
	v_exp_f32_e32 v4, v4
	v_exp_f32_e32 v5, v5
	v_exp_f32_e32 v6, v6
	v_exp_f32_e32 v7, v7
	v_fma_f32 v36, v36, v152, v152
	v_fma_f32 v37, v37, v152, v152
	v_fma_f32 v38, v38, v152, v152
	v_fma_f32 v39, v39, v152, v152
	v_fma_f32 v4, v4, v152, v152
	v_fma_f32 v5, v5, v152, v152
	v_fma_f32 v6, v6, v152, v152
	v_fma_f32 v7, v7, v152, v152
	v_rcp_f32_e32 v36, v36
	v_rcp_f32_e32 v37, v37
	v_rcp_f32_e32 v38, v38
	v_rcp_f32_e32 v39, v39
	v_rcp_f32_e32 v4, v4
	v_rcp_f32_e32 v5, v5
	v_rcp_f32_e32 v6, v6
	v_rcp_f32_e32 v7, v7
	v_cvt_pk_f16_f32 v36, v36, v37
	v_cvt_pk_f16_f32 v37, v38, v39
	v_cvt_pk_f16_f32 v38, v4, v5
	v_cvt_pk_f16_f32 v39, v6, v7
	global_store_dwordx4 v[174:175], v[36:39], off offset:256
	v_add_co_u32_e64 v172, s[0:1], s96, v162
	s_nop 1
	v_addc_co_u32_e64 v173, s[0:1], 0, v163, s[0:1]
	v_fma_f32 v100, v100, v182, v140
	v_fma_f32 v101, v101, v182, v141
	v_fma_f32 v102, v102, v182, v142
	v_fma_f32 v103, v103, v182, v143
	v_fma_f32 v64, v64, v182, v136
	v_fma_f32 v65, v65, v182, v137
	v_fma_f32 v66, v66, v182, v138
	v_fma_f32 v67, v67, v182, v139
	v_exp_f32_e32 v100, v100
	v_exp_f32_e32 v101, v101
	v_exp_f32_e32 v102, v102
	v_exp_f32_e32 v103, v103
	v_exp_f32_e32 v64, v64
	v_exp_f32_e32 v65, v65
	v_exp_f32_e32 v66, v66
	v_exp_f32_e32 v67, v67
	v_fma_f32 v100, v100, v152, v152
	v_fma_f32 v101, v101, v152, v152
	v_fma_f32 v102, v102, v152, v152
	v_fma_f32 v103, v103, v152, v152
	v_fma_f32 v64, v64, v152, v152
	v_fma_f32 v65, v65, v152, v152
	v_fma_f32 v66, v66, v152, v152
	v_fma_f32 v67, v67, v152, v152
	v_rcp_f32_e32 v100, v100
	v_rcp_f32_e32 v101, v101
	v_rcp_f32_e32 v102, v102
	v_rcp_f32_e32 v103, v103
	v_rcp_f32_e32 v64, v64
	v_rcp_f32_e32 v65, v65
	v_rcp_f32_e32 v66, v66
	v_rcp_f32_e32 v67, v67
	v_cvt_pk_f16_f32 v100, v100, v101
	v_cvt_pk_f16_f32 v101, v102, v103
	v_cvt_pk_f16_f32 v102, v64, v65
	v_cvt_pk_f16_f32 v103, v66, v67
	global_store_dwordx4 v[172:173], v[100:103], off
	v_fma_f32 v32, v32, v182, v132
	v_fma_f32 v33, v33, v182, v133
	v_fma_f32 v34, v34, v182, v134
	v_fma_f32 v35, v35, v182, v135
	v_fma_f32 v0, v0, v182, v96
	v_fma_f32 v1, v1, v182, v97
	v_fma_f32 v2, v2, v182, v98
	v_fma_f32 v3, v3, v182, v99
	v_exp_f32_e32 v32, v32
	v_exp_f32_e32 v33, v33
	v_exp_f32_e32 v34, v34
	v_exp_f32_e32 v35, v35
	v_exp_f32_e32 v0, v0
	v_exp_f32_e32 v1, v1
	v_exp_f32_e32 v2, v2
	v_exp_f32_e32 v3, v3
	v_fma_f32 v32, v32, v152, v152
	v_fma_f32 v33, v33, v152, v152
	v_fma_f32 v34, v34, v152, v152
	v_fma_f32 v35, v35, v152, v152
	v_fma_f32 v0, v0, v152, v152
	v_fma_f32 v1, v1, v152, v152
	v_fma_f32 v2, v2, v152, v152
	v_fma_f32 v3, v3, v152, v152
	v_rcp_f32_e32 v32, v32
	v_rcp_f32_e32 v33, v33
	v_rcp_f32_e32 v34, v34
	v_rcp_f32_e32 v35, v35
	v_rcp_f32_e32 v0, v0
	v_rcp_f32_e32 v1, v1
	v_rcp_f32_e32 v2, v2
	v_rcp_f32_e32 v3, v3
	v_cvt_pk_f16_f32 v32, v32, v33
	v_cvt_pk_f16_f32 v33, v34, v35
	v_cvt_pk_f16_f32 v34, v0, v1
	v_cvt_pk_f16_f32 v35, v2, v3
	global_store_dwordx4 v[172:173], v[32:35], off offset:256
	s_branch .Lp8_epi_done
.Lp8_noact:
	v_add_f32_e32 v128, v128, v140
	v_add_f32_e32 v129, v129, v141
	v_add_f32_e32 v130, v130, v142
	v_add_f32_e32 v131, v131, v143
	v_add_f32_e32 v92, v92, v136
	v_add_f32_e32 v93, v93, v137
	v_add_f32_e32 v94, v94, v138
	v_add_f32_e32 v95, v95, v139
	v_cvt_pk_f16_f32 v128, v128, v129
	v_cvt_pk_f16_f32 v129, v130, v131
	v_cvt_pk_f16_f32 v130, v92, v93
	v_cvt_pk_f16_f32 v131, v94, v95
	global_store_dwordx4 v[162:163], v[128:131], off
	v_add_f32_e32 v60, v60, v132
	v_add_f32_e32 v61, v61, v133
	v_add_f32_e32 v62, v62, v134
	v_add_f32_e32 v63, v63, v135
	v_add_f32_e32 v28, v28, v96
	v_add_f32_e32 v29, v29, v97
	v_add_f32_e32 v30, v30, v98
	v_add_f32_e32 v31, v31, v99
	v_cvt_pk_f16_f32 v60, v60, v61
	v_cvt_pk_f16_f32 v61, v62, v63
	v_cvt_pk_f16_f32 v62, v28, v29
	v_cvt_pk_f16_f32 v63, v30, v31
	global_store_dwordx4 v[162:163], v[60:63], off offset:256
	v_add_co_u32_e64 v172, s[0:1], s71, v162
	s_nop 1
	v_addc_co_u32_e64 v173, s[0:1], 0, v163, s[0:1]
	v_add_f32_e32 v124, v124, v140
	v_add_f32_e32 v125, v125, v141
	v_add_f32_e32 v126, v126, v142
	v_add_f32_e32 v127, v127, v143
	v_add_f32_e32 v88, v88, v136
	v_add_f32_e32 v89, v89, v137
	v_add_f32_e32 v90, v90, v138
	v_add_f32_e32 v91, v91, v139
	v_cvt_pk_f16_f32 v124, v124, v125
	v_cvt_pk_f16_f32 v125, v126, v127
	v_cvt_pk_f16_f32 v126, v88, v89
	v_cvt_pk_f16_f32 v127, v90, v91
	global_store_dwordx4 v[172:173], v[124:127], off
	v_add_f32_e32 v56, v56, v132
	v_add_f32_e32 v57, v57, v133
	v_add_f32_e32 v58, v58, v134
	v_add_f32_e32 v59, v59, v135
	v_add_f32_e32 v24, v24, v96
	v_add_f32_e32 v25, v25, v97
	v_add_f32_e32 v26, v26, v98
	v_add_f32_e32 v27, v27, v99
	v_cvt_pk_f16_f32 v56, v56, v57
	v_cvt_pk_f16_f32 v57, v58, v59
	v_cvt_pk_f16_f32 v58, v24, v25
	v_cvt_pk_f16_f32 v59, v26, v27
	global_store_dwordx4 v[172:173], v[56:59], off offset:256
	s_mov_b32 s0, 0x10000
	v_add_co_u32_e64 v174, s[0:1], s0, v162
	s_nop 1
	v_addc_co_u32_e64 v175, s[0:1], 0, v163, s[0:1]
	v_add_f32_e32 v120, v120, v140
	v_add_f32_e32 v121, v121, v141
	v_add_f32_e32 v122, v122, v142
	v_add_f32_e32 v123, v123, v143
	v_add_f32_e32 v84, v84, v136
	v_add_f32_e32 v85, v85, v137
	v_add_f32_e32 v86, v86, v138
	v_add_f32_e32 v87, v87, v139
	v_cvt_pk_f16_f32 v120, v120, v121
; __device__ __forceinline__ float sigm(float x) { return __builtin_amdgcn_rcpf(1.0f + __expf(-x)); }
;     __device__ __forceinline__ void operator()(const f32x4 (&acc)[2][2][4][2], const pg8::Unit& u, int wr, int wc, int fr, int fq) const {
;     ...
;             for (int n = 0; n < 2; ++n) bva[bj][n] = *(const f32x4*)(bp + bj * 128 + 4 * n);
; #pragma unroll
;         for (int bj = 0; bj < 2; ++bj)
; #pragma unroll
;             for (int n = 0; n < 2; ++n) {
;                 const f32x4 bv = bva[bj][n];
; #pragma unroll
;                 for (int ai = 0; ai < 2; ++ai)
; #pragma unroll
;                     for (int m = 0; m < 4; ++m) {
;                         f32x4 v = acc[ai][bj][m][n] + bv;
; #pragma unroll
;                         for (int j = 0; j < 4; ++j) { const float sg = sc * sigm(v[j]); v[j] = act ? sg : v[j]; }
;                         u32x2 w; w.x = pk_f16(v[0], v[1]); w.y = pk_f16(v[2], v[3]);
;                         *(u32x2*)(base + (size_t)(ai * 128 + m * 16) * RW + bj * 128 + 4 * n) = w;
;                     }
	v_cvt_pk_f16_f32 v121, v122, v123
	v_cvt_pk_f16_f32 v122, v84, v85
	v_cvt_pk_f16_f32 v123, v86, v87
	global_store_dwordx4 v[174:175], v[120:123], off
	v_add_f32_e32 v52, v52, v132
	v_add_f32_e32 v53, v53, v133
	v_add_f32_e32 v54, v54, v134
	v_add_f32_e32 v55, v55, v135
	v_add_f32_e32 v20, v20, v96
	v_add_f32_e32 v21, v21, v97
	v_add_f32_e32 v22, v22, v98
	v_add_f32_e32 v23, v23, v99
	v_cvt_pk_f16_f32 v52, v52, v53
	v_cvt_pk_f16_f32 v53, v54, v55
	v_cvt_pk_f16_f32 v54, v20, v21
	v_cvt_pk_f16_f32 v55, v22, v23
	global_store_dwordx4 v[174:175], v[52:55], off offset:256
	s_mov_b32 s0, 0x18000
	v_add_co_u32_e64 v172, s[0:1], s0, v162
	s_nop 1
	v_addc_co_u32_e64 v173, s[0:1], 0, v163, s[0:1]
	v_add_f32_e32 v116, v116, v140
	v_add_f32_e32 v117, v117, v141
	v_add_f32_e32 v118, v118, v142
	v_add_f32_e32 v119, v119, v143
	v_add_f32_e32 v80, v80, v136
	v_add_f32_e32 v81, v81, v137
	v_add_f32_e32 v82, v82, v138
	v_add_f32_e32 v83, v83, v139
	v_cvt_pk_f16_f32 v116, v116, v117
	v_cvt_pk_f16_f32 v117, v118, v119
	v_cvt_pk_f16_f32 v118, v80, v81
	v_cvt_pk_f16_f32 v119, v82, v83
	global_store_dwordx4 v[172:173], v[116:119], off
	v_add_f32_e32 v48, v48, v132
	v_add_f32_e32 v49, v49, v133
	v_add_f32_e32 v50, v50, v134
	v_add_f32_e32 v51, v51, v135
	v_add_f32_e32 v16, v16, v96
	v_add_f32_e32 v17, v17, v97
	v_add_f32_e32 v18, v18, v98
	v_add_f32_e32 v19, v19, v99
	v_cvt_pk_f16_f32 v48, v48, v49
	v_cvt_pk_f16_f32 v49, v50, v51
	v_cvt_pk_f16_f32 v50, v16, v17
	v_cvt_pk_f16_f32 v51, v18, v19
	global_store_dwordx4 v[172:173], v[48:51], off offset:256
	v_add_co_u32_e64 v174, s[0:1], s85, v162
	s_nop 1
	v_addc_co_u32_e64 v175, s[0:1], 0, v163, s[0:1]
	v_add_f32_e32 v112, v112, v140
	v_add_f32_e32 v113, v113, v141
	v_add_f32_e32 v114, v114, v142
	v_add_f32_e32 v115, v115, v143
	v_add_f32_e32 v76, v76, v136
	v_add_f32_e32 v77, v77, v137
	v_add_f32_e32 v78, v78, v138
	v_add_f32_e32 v79, v79, v139
	v_cvt_pk_f16_f32 v112, v112, v113
	v_cvt_pk_f16_f32 v113, v114, v115
	v_cvt_pk_f16_f32 v114, v76, v77
	v_cvt_pk_f16_f32 v115, v78, v79
	global_store_dwordx4 v[174:175], v[112:115], off
	v_add_f32_e32 v44, v44, v132
	v_add_f32_e32 v45, v45, v133
	v_add_f32_e32 v46, v46, v134
	v_add_f32_e32 v47, v47, v135
	v_add_f32_e32 v12, v12, v96
	v_add_f32_e32 v13, v13, v97
	v_add_f32_e32 v14, v14, v98
	v_add_f32_e32 v15, v15, v99
	v_cvt_pk_f16_f32 v44, v44, v45
	v_cvt_pk_f16_f32 v45, v46, v47
	v_cvt_pk_f16_f32 v46, v12, v13
	v_cvt_pk_f16_f32 v47, v14, v15
	global_store_dwordx4 v[174:175], v[44:47], off offset:256
	v_add_co_u32_e64 v172, s[0:1], s94, v162
	s_nop 1
	v_addc_co_u32_e64 v173, s[0:1], 0, v163, s[0:1]
	v_add_f32_e32 v108, v108, v140
	v_add_f32_e32 v109, v109, v141
	v_add_f32_e32 v110, v110, v142
	v_add_f32_e32 v111, v111, v143
	v_add_f32_e32 v72, v72, v136
	v_add_f32_e32 v73, v73, v137
	v_add_f32_e32 v74, v74, v138
	v_add_f32_e32 v75, v75, v139
	v_cvt_pk_f16_f32 v108, v108, v109
	v_cvt_pk_f16_f32 v109, v110, v111
	v_cvt_pk_f16_f32 v110, v72, v73
	v_cvt_pk_f16_f32 v111, v74, v75
	global_store_dwordx4 v[172:173], v[108:111], off
	v_add_f32_e32 v40, v40, v132
	v_add_f32_e32 v41, v41, v133
	v_add_f32_e32 v42, v42, v134
	v_add_f32_e32 v43, v43, v135
	v_add_f32_e32 v8, v8, v96
	v_add_f32_e32 v9, v9, v97
	v_add_f32_e32 v10, v10, v98
	v_add_f32_e32 v11, v11, v99
	v_cvt_pk_f16_f32 v40, v40, v41
	v_cvt_pk_f16_f32 v41, v42, v43
	v_cvt_pk_f16_f32 v42, v8, v9
	v_cvt_pk_f16_f32 v43, v10, v11
	global_store_dwordx4 v[172:173], v[40:43], off offset:256
	v_add_co_u32_e64 v174, s[0:1], s95, v162
	s_nop 1
	v_addc_co_u32_e64 v175, s[0:1], 0, v163, s[0:1]
	v_add_f32_e32 v104, v104, v140
	v_add_f32_e32 v105, v105, v141
	v_add_f32_e32 v106, v106, v142
	v_add_f32_e32 v107, v107, v143
	v_add_f32_e32 v68, v68, v136
	v_add_f32_e32 v69, v69, v137
	v_add_f32_e32 v70, v70, v138
	v_add_f32_e32 v71, v71, v139
	v_cvt_pk_f16_f32 v104, v104, v105
	v_cvt_pk_f16_f32 v105, v106, v107
	v_cvt_pk_f16_f32 v106, v68, v69
	v_cvt_pk_f16_f32 v107, v70, v71
	global_store_dwordx4 v[174:175], v[104:107], off
	v_add_f32_e32 v36, v36, v132
	v_add_f32_e32 v37, v37, v133
	v_add_f32_e32 v38, v38, v134
	v_add_f32_e32 v39, v39, v135
	v_add_f32_e32 v4, v4, v96
	v_add_f32_e32 v5, v5, v97
	v_add_f32_e32 v6, v6, v98
	v_add_f32_e32 v7, v7, v99
	v_cvt_pk_f16_f32 v36, v36, v37
	v_cvt_pk_f16_f32 v37, v38, v39
	v_cvt_pk_f16_f32 v38, v4, v5
	v_cvt_pk_f16_f32 v39, v6, v7
	global_store_dwordx4 v[174:175], v[36:39], off offset:256
	v_add_co_u32_e64 v172, s[0:1], s96, v162
	s_nop 1
	v_addc_co_u32_e64 v173, s[0:1], 0, v163, s[0:1]
	v_add_f32_e32 v100, v100, v140
	v_add_f32_e32 v101, v101, v141
	v_add_f32_e32 v102, v102, v142
	v_add_f32_e32 v103, v103, v143
	v_add_f32_e32 v64, v64, v136
	v_add_f32_e32 v65, v65, v137
	v_add_f32_e32 v66, v66, v138
	v_add_f32_e32 v67, v67, v139
	v_cvt_pk_f16_f32 v100, v100, v101
	v_cvt_pk_f16_f32 v101, v102, v103
	v_cvt_pk_f16_f32 v102, v64, v65
	v_cvt_pk_f16_f32 v103, v66, v67
	global_store_dwordx4 v[172:173], v[100:103], off
	v_add_f32_e32 v32, v32, v132
	v_add_f32_e32 v33, v33, v133
	v_add_f32_e32 v34, v34, v134
	v_add_f32_e32 v35, v35, v135
	v_add_f32_e32 v0, v0, v96
	v_add_f32_e32 v1, v1, v97
	v_add_f32_e32 v2, v2, v98
	v_add_f32_e32 v3, v3, v99
	v_cvt_pk_f16_f32 v32, v32, v33
	v_cvt_pk_f16_f32 v33, v34, v35
	v_cvt_pk_f16_f32 v34, v0, v1
	v_cvt_pk_f16_f32 v35, v2, v3
	global_store_dwordx4 v[172:173], v[32:35], off offset:256
